# scan: skip redundant D-gate LDS-DMA loads on 6 of 8 waves (W1 count adjusted)
# speedup vs baseline: 1.0021x; 1.0021x over previous
; #define LAS __attribute__((address_space(3)))
; DI bf16_t* wz_ptr(const Params& p) { return (bf16_t*)p.out + (size_t)T * DM; }
; DI bf16_t* zs_ptr(const Params& p) { return woutb_ptr(p) + (size_t)2048 * 4096; }
; DI unsigned lds_addr_of(const void* p) { return (unsigned)(size_t)p; }
; #define PH_BEGIN(k) if (p.ph_lo <= (k) && (k) < p.ph_hi) { if ((k) > p.ph_lo) SEAM(k); for (int rep_ = 0; rep_ < ((REPEAT_MASK >> (k)) & 1u ? 2 : 1); ++rep_) { if (rep_) grid.sync();
; __device__ void phase_scan(const Params& p, unsigned char* shm) {
;     const int tid = threadIdx.x, wid = __builtin_amdgcn_readfirstlane(tid >> 6), lane = tid & 63, fr = lane & 15, fq = lane >> 4;
;     const int dirw = wid >> 2, wq = wid & 3;
;     LAS unsigned char* lds = (LAS unsigned char*)shm;
;     const unsigned char* qimg = p.ws + OFF_QIMG; const unsigned char* kimg = p.ws + OFF_KIMG; const unsigned char* aimg = p.ws + OFF_AIMG;
;     const float* dg = (const float*)(p.ws + OFF_E12); const bf16_t* Vg = (const bf16_t*)(p.ws + OFF_VB); bf16_t* O = (bf16_t*)(p.ws + OFF_O);
;     const unsigned sbase = lds_addr_of(shm);
;     constexpr int L_QA = 0, L_QB = 32768, L_KA = 65536, L_KB = 98304, L_V = 131072, L_D = 147456, L_A = 149504;
;     ...
;     for (int item = blockIdx.x; item < 192; item += gridDim.x) {
;         const int xcd = item & 7, idx = item >> 3; int grp, slice;
;         if (idx < 16) { grp = xcd; slice = idx; } else { grp = 8 + (xcd >> 1); slice = (xcd & 1) * 8 + (idx - 16); }
;         int seq, h; if (grp < 8) { seq = 1 + (grp >> 2); h = grp & 3; } else { seq = 0; h = grp - 8; }
;         const int chunk0 = seq == 0 ? 0 : (seq == 1 ? 128 : 384), N = seq == 0 ? 128 : 256;
;         const int colbase = h * 1024 + slice * 64;
; __global__ void __launch_bounds__(512) fwd_megakernel(Params p) {
;     ...
;     PH_BEGIN(8) if (gridDim.x == 256 && blockIdx.x >= 192) {
;                     pg8::Gemm g{(const bf16_t*)p.out, wz_ptr(p), ZPRE_ROWS, 4096, 2048}; S.init(g.M, g.N, 64, (int)blockIdx.x - 192);
;                     EpiZs E{zs_ptr(p)}; pg8::gemm_phase(lds, g, S, E);
;                 } else phase_scan(p, shm); PH_END
.LBB0_677:
	s_cmpk_lg_i32 s30, 0x100
	s_cselect_b64 s[0:1], -1, 0
	s_cmpk_lt_u32 s2, 0xc0
	s_cselect_b64 s[4:5], -1, 0
	s_or_b64 s[0:1], s[4:5], s[0:1]
	v_and_b32_e32 v138, 15, v136
	v_lshlrev_b32_e32 v137, 2, v136
	v_lshrrev_b32_e32 v134, 1, v136
	s_mov_b64 s[4:5], -1
	s_and_b64 vcc, exec, s[0:1]
	s_cbranch_vccz .LBB0_702
	v_writelane_b32 v246, s94, 0
	s_cmpk_gt_i32 s2, 0xbf
	v_readfirstlane_b32 s0, v136
	v_writelane_b32 v246, s95, 1
	v_writelane_b32 v246, s92, 2
	v_writelane_b32 v246, s90, 3
	s_nop 1
	v_writelane_b32 v246, s91, 4
	s_cbranch_scc1 .LBB0_701
	s_lshr_b32 s98, s0, 6
	v_bfe_u32 v6, v136, 4, 2
	v_lshlrev_b32_e32 v2, 3, v6
	v_mov_b32_e32 v15, 0xffff
	v_cmp_eq_u32_e32 vcc, v138, v2
	v_or_b32_e32 v17, 2, v2
	v_or_b32_e32 v19, 4, v2
	v_cndmask_b32_e32 v16, 0, v15, vcc
	v_cmp_le_u32_e32 vcc, v138, v2
	v_or_b32_e32 v21, 6, v2
	v_xor_b32_e32 v10, v6, v138
	v_cndmask_b32_e32 v16, -1, v16, vcc
	v_cmp_eq_u32_e32 vcc, v138, v17
	v_lshrrev_b32_e32 v3, 2, v138
	v_lshlrev_b32_e32 v135, 4, v10
	v_cndmask_b32_e32 v18, 0, v15, vcc
	v_cmp_le_u32_e32 vcc, v138, v17
	v_or_b32_e32 v10, 16, v138
	v_mov_b32_e32 v89, 0
	v_cndmask_b32_e32 v18, -1, v18, vcc
	v_cmp_eq_u32_e32 vcc, v138, v19
	v_or_b32_e32 v3, v2, v3
	v_lshlrev_b32_e32 v8, 7, v3
	v_cndmask_b32_e32 v20, 0, v15, vcc
	v_cmp_le_u32_e32 vcc, v138, v19
	v_mov_b32_e32 v3, v89
	v_lshl_add_u64 v[4:5], s[26:27], 0, v[2:3]
	v_cndmask_b32_e32 v20, -1, v20, vcc
	v_cmp_eq_u32_e32 vcc, v138, v21
	v_or_b32_e32 v23, 32, v2
	v_or_b32_e32 v24, 34, v2
	v_cndmask_b32_e32 v22, 0, v15, vcc
	v_cmp_le_u32_e32 vcc, v138, v21
	v_or_b32_e32 v25, 36, v2
	v_or_b32_e32 v26, 38, v2
	v_cndmask_b32_e32 v22, -1, v22, vcc
	v_cmp_eq_u32_e32 vcc, v10, v2
	v_or_b32_e32 v11, 32, v138
	s_add_u32 s18, s26, 0x32000000
	v_cndmask_b32_e32 v27, 0, v15, vcc
	v_cmp_le_u32_e32 vcc, v10, v2
	v_or_b32_e32 v12, 48, v138
	s_addc_u32 s19, s27, 0
	v_cndmask_b32_e32 v2, -1, v27, vcc
	v_cmp_eq_u32_e32 vcc, v10, v17
	s_add_u32 s20, s26, 0x28000000
	s_addc_u32 s21, s27, 0
	v_cndmask_b32_e32 v27, 0, v15, vcc
	v_cmp_le_u32_e32 vcc, v10, v17
	v_lshlrev_b32_e32 v1, 4, v138
	s_cmp_lg_u32 0, -1
	v_cndmask_b32_e32 v17, -1, v27, vcc
	v_cmp_eq_u32_e32 vcc, v10, v19
	s_waitcnt lgkmcnt(0)
; DI unsigned lds_addr_of(const void* p) { return (unsigned)(size_t)p; }
; __device__ void phase_scan(const Params& p, unsigned char* shm) {
;     ...
;     const unsigned char* qimg = p.ws + OFF_QIMG; const unsigned char* kimg = p.ws + OFF_KIMG; const unsigned char* aimg = p.ws + OFF_AIMG;
;     const float* dg = (const float*)(p.ws + OFF_E12); const bf16_t* Vg = (const bf16_t*)(p.ws + OFF_VB); bf16_t* O = (bf16_t*)(p.ws + OFF_O);
;     const unsigned sbase = lds_addr_of(shm);
;     constexpr int L_QA = 0, L_QB = 32768, L_KA = 65536, L_KB = 98304, L_V = 131072, L_D = 147456, L_A = 149504;
;     ...
;     for (int item = blockIdx.x; item < 192; item += gridDim.x) {
;         const int xcd = item & 7, idx = item >> 3; int grp, slice;
;         if (idx < 16) { grp = xcd; slice = idx; } else { grp = 8 + (xcd >> 1); slice = (xcd & 1) * 8 + (idx - 16); }
;         int seq, h; if (grp < 8) { seq = 1 + (grp >> 2); h = grp & 3; } else { seq = 0; h = grp - 8; }
;         const int chunk0 = seq == 0 ? 0 : (seq == 1 ? 128 : 384), N = seq == 0 ? 128 : 256;
;         const int colbase = h * 1024 + slice * 64;
;         f32x4 S[16];
; #pragma unroll
;         for (int i = 0; i < 16; ++i) S[i] = (f32x4){0.f, 0.f, 0.f, 0.f};
	v_bitop3_b32 v13, v6, v138, 4 bitop3:0x36
	v_lshl_or_b32 v7, v6, 9, v1
	v_cndmask_b32_e32 v27, 0, v15, vcc
	v_cmp_le_u32_e32 vcc, v10, v19
	v_lshlrev_b32_e32 v1, 4, v136
	s_cselect_b32 s1, 0, 0
	v_cndmask_b32_e32 v19, -1, v27, vcc
	v_cmp_eq_u32_e32 vcc, v10, v21
	s_lshr_b32 s16, s0, 8
	v_and_b32_e32 v3, 7, v134
	v_cndmask_b32_e32 v27, 0, v15, vcc
	v_cmp_le_u32_e32 vcc, v10, v21
	v_lshlrev_b32_e32 v139, 4, v13
	v_bitop3_b32 v13, v6, v138, 8 bitop3:0x36
	v_cndmask_b32_e32 v21, -1, v27, vcc
	v_cmp_eq_u32_e32 vcc, v11, v24
	v_and_b32_e32 v0, 63, v136
	v_and_b32_e32 v88, 0x70, v1
	v_cndmask_b32_e32 v27, 0, v15, vcc
	v_cmp_le_u32_e32 vcc, v11, v24
	s_lshl_b32 s3, s16, 13
	v_lshlrev_b32_e32 v140, 4, v13
	v_cndmask_b32_e32 v27, -1, v27, vcc
	v_cmp_eq_u32_e32 vcc, v11, v25
	v_bitop3_b32 v13, v6, v138, 12 bitop3:0x36
	v_bitop3_b32 v14, v6, v134, 7 bitop3:0x78
	v_cndmask_b32_e32 v28, 0, v15, vcc
	v_cmp_le_u32_e32 vcc, v11, v25
	v_bitop3_b32 v3, v6, v3, 4 bitop3:0x36
	s_lshr_b32 s22, s0, 6
	v_cndmask_b32_e32 v28, -1, v28, vcc
	v_cmp_eq_u32_e32 vcc, v11, v26
	v_lshl_add_u64 v[90:91], s[26:27], 0, v[88:89]
	v_lshlrev_b32_e32 v88, 4, v0
	v_cndmask_b32_e32 v29, 0, v15, vcc
	v_cmp_le_u32_e32 vcc, v11, v26
	s_add_i32 s1, s1, s3
	v_lshlrev_b32_e32 v141, 4, v13
	v_cndmask_b32_e32 v29, -1, v29, vcc
	v_cmp_eq_u32_e32 vcc, v12, v23
	v_lshlrev_b32_e32 v13, 7, v138
	v_lshlrev_b32_e32 v142, 4, v14
	v_cndmask_b32_e32 v30, 0, v15, vcc
	v_cmp_le_u32_e32 vcc, v12, v23
	v_lshlrev_b32_e32 v143, 4, v3
	v_lshlrev_b32_e32 v3, 7, v10
	v_cndmask_b32_e32 v23, -1, v30, vcc
	v_cmp_eq_u32_e32 vcc, v12, v24
	v_lshlrev_b32_e32 v6, 7, v11
	v_lshlrev_b32_e32 v14, 7, v12
	v_cndmask_b32_e32 v30, 0, v15, vcc
	v_cmp_le_u32_e32 vcc, v12, v24
	s_add_i32 s3, 0, 0x24800
	s_lshl_b32 s10, s22, 10
	v_cndmask_b32_e32 v24, -1, v30, vcc
	v_cmp_eq_u32_e32 vcc, v12, v25
	v_lshl_add_u64 v[0:1], s[26:27], 0, v[88:89]
	s_mov_b64 s[4:5], 0x3e800000
	v_cndmask_b32_e32 v30, 0, v15, vcc
	v_cmp_le_u32_e32 vcc, v12, v25
	v_add_u32_e32 v144, s3, v13
	v_add_u32_e32 v145, s3, v3
	v_cndmask_b32_e32 v25, -1, v30, vcc
	v_cmp_eq_u32_e32 vcc, v12, v26
	v_add_u32_e32 v146, s3, v6
	v_add_u32_e32 v147, s3, v14
	v_cndmask_b32_e32 v15, 0, v15, vcc
	v_cmp_le_u32_e32 vcc, v12, v26
	s_movk_i32 s3, 0xffc0
	v_mov_b32_e32 v26, s0
	s_cmpk_gt_u32 s0, 0xff
	v_lshl_add_u64 v[92:93], v[0:1], 0, s[4:5]
	v_bfi_b32 v26, s3, v26, v136
	s_cselect_b64 s[4:5], -1, 0
	s_bfe_u32 s3, s0, 0x10006
	s_mov_b32 s9, 0
	s_cmp_eq_u32 s3, 0
	s_cselect_b64 s[12:13], -1, 0
	s_mov_b32 s11, s9
	s_lshr_b32 s8, s0, 2
	v_lshl_add_u64 v[0:1], v[0:1], 0, s[10:11]
	s_mov_b64 s[14:15], 0x3c000000
	s_and_b32 s8, s8, 48
	v_lshl_add_u64 v[94:95], v[0:1], 0, s[14:15]
	v_and_or_b32 v0, v137, 12, s8
	v_lshlrev_b32_e32 v0, 1, v0
	s_add_i32 s1, s1, 0x20000
	s_lshl_b32 s8, s8, 1
	v_add3_u32 v149, s1, v8, v0
	v_lshl_add_u64 v[0:1], v[4:5], 0, s[8:9]
	s_lshl_b32 s8, s16, 10
	s_lshl_b32 s1, s16, 14
	s_add_i32 s8, s8, 0
	s_add_i32 s25, 0, 0x10000
	s_add_i32 s35, 0, 0x18000
	s_lshl_b32 s23, s3, 10
	s_add_i32 s24, s1, 0
	s_add_i32 s8, s8, 0x24000
	s_add_i32 s34, s25, s1
	s_add_i32 s1, s35, s1
	s_lshr_b32 s11, s0, 10
	s_bfe_u32 s16, s0, 0x40006
	s_mov_b64 s[14:15], 0x14000000
	s_cmpk_lt_u32 s0, 0x400
	v_lshl_add_u64 v[96:97], v[0:1], 0, s[14:15]
	s_cselect_b64 s[14:15], -1, 0
	s_lshl_b32 s36, s11, 14
	s_add_i32 s37, s22, 8
	s_add_i32 s73, s36, 0
	s_lshl_b32 s38, s16, 10
	s_lshr_b32 s62, s37, 4
	s_and_b32 s39, s37, 15
	s_cmpk_lt_u32 s0, 0x200
	v_lshl_or_b32 v0, s16, 11, v7
	v_mov_b32_e32 v1, v89
	s_cselect_b64 s[16:17], -1, 0
	s_add_i32 s40, s22, 16
	s_add_i32 s22, s22, 24
	v_lshl_add_u64 v[98:99], s[20:21], 0, v[0:1]
	v_lshl_or_b32 v0, s39, 11, v7
	s_and_b32 s41, s22, 15
	v_lshl_add_u64 v[100:101], s[20:21], 0, v[0:1]
	v_lshl_or_b32 v0, s41, 11, v7
	v_lshl_add_u64 v[102:103], s[20:21], 0, v[0:1]
	s_lshl_b32 s21, s37, 10
	s_lshr_b32 s63, s40, 4
	s_lshr_b32 s64, s22, 4
	s_and_b32 s44, s10, 0x3c00
	s_and_b32 s45, s21, 0x3c00
	s_lshl_b32 s21, s22, 10
	s_lshl_b32 s0, s62, 14
	s_lshl_b32 s40, s63, 14
	s_lshl_b32 s20, s64, 14
	v_or_b32_e32 v0, s44, v88
	s_and_b32 s52, s21, 0x3c00
	v_and_b32_e32 v9, 48, v136
	v_cndmask_b32_e32 v15, -1, v15, vcc
	v_cndmask_b32_e64 v4, 0, -1, s[4:5]
	s_add_i32 s74, s0, 0
	s_lshl_b32 s39, s39, 10
	s_add_i32 s75, s40, 0
	s_add_i32 s76, s20, 0
	s_lshl_b32 s41, s41, 10
	v_lshl_add_u64 v[104:105], s[18:19], 0, v[0:1]
	s_add_i32 s77, s25, s36
	v_or_b32_e32 v0, s45, v88
	s_add_i32 s78, s25, s0
	s_add_i32 s79, s25, s40
	v_or_b32_e32 v88, s52, v88
	s_add_i32 s80, s25, s20
	s_add_i32 s69, s35, s36
	s_add_i32 s70, s35, s0
	s_add_i32 s71, s35, s40
	s_add_i32 s72, s35, s20
	s_add_i32 s68, s23, 0
	v_ashrrev_i32_e32 v148, 3, v26
	v_lshl_add_u64 v[106:107], s[18:19], 0, v[0:1]
	v_lshl_add_u64 v[108:109], s[18:19], 0, v[88:89]
	v_lshl_add_u32 v88, v138, 8, s24
	v_lshl_add_u32 v150, v10, 8, s24
	v_lshl_add_u32 v151, v11, 8, s24
	v_lshl_add_u32 v152, v12, 8, s24
	v_add_u32_e32 v153, s34, v13
	v_add_u32_e32 v154, s34, v3
	v_add_u32_e32 v155, s34, v6
	v_add_u32_e32 v156, s34, v14
	v_xor_b32_e32 v157, v16, v4
	v_xor_b32_e32 v158, v18, v4
	v_xor_b32_e32 v159, v20, v4
	v_xor_b32_e32 v160, v22, v4
	v_xor_b32_e32 v161, v2, v4
	v_xor_b32_e32 v162, v17, v4
	v_xor_b32_e32 v163, v19, v4
	v_xor_b32_e32 v164, v21, v4
	v_xor_b32_e32 v165, v27, v4
	v_xor_b32_e32 v166, v28, v4
	v_xor_b32_e32 v167, v29, v4
	v_xor_b32_e32 v168, v23, v4
	v_xor_b32_e32 v169, v24, v4
	v_xor_b32_e32 v170, v25, v4
	v_xor_b32_e32 v171, v15, v4
	v_add_u32_e32 v172, s1, v13
	v_add_u32_e32 v173, s1, v3
	v_add_u32_e32 v174, s1, v6
	v_add_u32_e32 v175, s1, v14
	s_add_i32 s65, s64, -8
	s_add_i32 s66, s63, -8
	s_movk_i32 s67, 0x180
	s_mov_b64 s[18:19], 0x100
	s_add_i32 s68, s68, 0x24000
	s_add_i32 s69, s69, s44
	s_add_i32 s70, s70, s45
	s_add_i32 s71, s71, s44
	s_add_i32 s72, s72, s52
	s_mov_b64 s[20:21], 0x4000
	s_mov_b64 s[22:23], 0x60000
	s_mov_b64 s[24:25], 0x40000
	s_mov_b64 s[36:37], 0x20000
	s_add_i32 s73, s73, s38
	s_add_i32 s74, s74, s39
	s_add_i32 s75, s75, s38
	s_add_i32 s76, s76, s41
	s_add_i32 s77, s77, s44
	s_add_i32 s78, s78, s45
	s_add_i32 s79, s79, s44
	s_add_i32 s80, s80, s52
	v_add_u32_e32 v176, s8, v9
	s_mov_b32 s81, s2
	s_branch .LBB0_681

; #define SC_WV(n) asm volatile("s_waitcnt vmcnt(" #n ") lgkmcnt(0)" ::: "memory")
; #define SC_BAR __builtin_amdgcn_s_barrier()
; #define SC_LD_D(m_) do { const int _dir = wid & 1; \
;             __builtin_amdgcn_global_load_lds((const unsigned*)(dg + (size_t)SC_UNIT(_dir, m_) * 256 + lane * 4), (LAS unsigned*)(lds + L_D + _dir * 1024), 16, 0, 0); } while (0)
; #define SC_LD_A(m_) do { __builtin_amdgcn_global_load_lds((const unsigned*)(aimg + ((size_t)(chunk0 + (m_)) * 4 + h) * 8192 + wid * 1024 + lane * 16), (LAS unsigned*)(lds + L_A + wid * 1024), 16, 0, 0); } while (0)
; __device__ void phase_scan(const Params& p, unsigned char* shm) {
;     ...
;             const int c = dirw ? (N - 1 - n) : n, row0 = (chunk0 + c) * 64, m = (n + 1 < N) ? n + 1 : n;
;             const bool first = n < (N >> 1);
;             if (n == (N >> 1)) SC_WV(0); else SC_WV(8);
;             SC_BAR;
;             SC_LD_D(n); SC_LD_KH(1, n); SC_LD_A(n);
;             bf16x8 vb[2];
;             { const unsigned ad = sbase + (unsigned)L_V + (unsigned)(dirw * 8192 + (8 * fq + (fr >> 2)) * 128 + (wq * 16 + (fr & 3) * 4) * 2);
;               s16x4 r0, r1, r2, r3;
;               asm volatile("ds_read_b64_tr_b16 %0, %4\n\tds_read_b64_tr_b16 %1, %4 offset:512\n\tds_read_b64_tr_b16 %2, %4 offset:4096\n\tds_read_b64_tr_b16 %3, %4 offset:4608\n\ts_waitcnt lgkmcnt(0)"
;                            : "=&v"(r0), "=&v"(r1), "=&v"(r2), "=&v"(r3) : "v"(ad) : "memory");
;               vb[0] = __builtin_shufflevector(r0, r1, 0, 1, 2, 3, 4, 5, 6, 7); vb[1] = __builtin_shufflevector(r2, r3, 0, 1, 2, 3, 4, 5, 6, 7); }
;             f32x4 o[4];
; #pragma unroll
;             for (int mt = 0; mt < 4; ++mt) o[mt] = (f32x4){0.f, 0.f, 0.f, 0.f};
;             SC_OINTER(L_QA, 0);
;             SC_WV(10); SC_BAR;
;             SC_LD_QH(0, m); SC_LD_V(m);
;             bf16_t* op = O + (size_t)(row0 + fr) * EI + colbase + wq * 16 + 4 * fq;
;             u32x2 opv[4];
;             asm volatile("" ::: "memory");
;             if (!first) {
; #pragma unroll
;                 for (int mt = 0; mt < 4; ++mt) asm volatile("global_load_dwordx2 %0, %1, off" : "=&v"(opv[mt]) : "v"(op + (size_t)(16 * mt) * EI) : "memory");
;             }
;             asm volatile("" ::: "memory");
;             SC_OINTER(L_QB, 1);
;             if (first) SC_WV(11); else SC_WV(15);
.LBB0_685:
	s_and_b64 s[44:45], s[4:5], exec
	s_cselect_b32 s60, s88, s1
	s_add_i32 s60, s60, s83
	s_add_i32 s0, s1, 1
	s_cmp_lt_u32 s0, s82
	s_cselect_b32 s61, s0, s1
	s_cmp_ge_u32 s1, s97
	s_cselect_b64 s[58:59], -1, 0
	s_and_b64 s[44:45], s[12:13], exec
	s_cselect_b32 s8, s1, s88
	s_add_i32 s8, s8, s83
	s_lshl_b32 s8, s8, 3
	s_or_b32 s44, s8, s90
	s_ashr_i32 s45, s44, 31
	s_lshl_b64 s[44:45], s[44:45], 10
	s_and_b64 s[52:53], s[14:15], exec
	s_cselect_b32 s8, s1, s88
	s_add_i32 s8, s8, s83
	s_lshl_b32 s8, s8, 3
	s_add_i32 s52, s8, s84
	s_ashr_i32 s53, s52, 31
	s_lshl_b64 s[52:53], s[52:53], 15
	s_and_b64 s[54:55], s[16:17], exec
	s_cselect_b32 s8, s1, s88
	s_add_i32 s8, s8, s83
	s_lshl_b32 s8, s8, 3
	s_mov_b32 m0, s68
	s_add_i32 s54, s8, s85
	v_lshl_add_u64 v[64:65], v[92:93], 0, s[44:45]
	s_ashr_i32 s55, s54, 31
	s_barrier
	s_cmp_gt_u32 s98, 1
	s_cbranch_scc1 .Lskip_dload
	global_load_lds_dwordx4 v[64:65], off
.Lskip_dload:
	v_lshl_add_u64 v[64:65], v[104:105], 0, s[52:53]
	s_lshl_b64 s[54:55], s[54:55], 15
	v_lshl_add_u64 v[64:65], v[64:65], 0, s[20:21]
	s_mov_b32 m0, s69
	s_ashr_i32 s41, s40, 31
	global_load_lds_dwordx4 v[64:65], off
	v_lshl_add_u64 v[64:65], v[106:107], 0, s[54:55]
	s_lshl_b64 s[56:57], s[40:41], 15
	v_lshl_add_u64 v[64:65], v[64:65], 0, s[20:21]
	s_mov_b32 m0, s70
	s_ashr_i32 s39, s38, 31
	global_load_lds_dwordx4 v[64:65], off
	v_lshl_add_u64 v[64:65], v[104:105], 0, s[56:57]
	s_lshl_b64 vcc, s[38:39], 15
	v_lshl_add_u64 v[64:65], v[64:65], 0, s[20:21]
	s_mov_b32 m0, s71
	s_add_i32 s8, s83, s1
	global_load_lds_dwordx4 v[64:65], off
	v_lshl_add_u64 v[64:65], v[108:109], 0, vcc
	s_lshl_b64 s[34:35], s[8:9], 15
	s_add_i32 s8, s89, 0x24800
	v_lshl_add_u64 v[64:65], v[64:65], 0, s[20:21]
	s_mov_b32 m0, s72
	v_add_u32_e32 v177, v88, v135
	global_load_lds_dwordx4 v[64:65], off
	v_lshl_add_u64 v[64:65], v[120:121], 0, s[34:35]
	s_mov_b32 m0, s8
	s_not_b32 s8, s61
	global_load_lds_dwordx4 v[64:65], off
	s_add_i32 s8, s82, s8
	s_and_b64 s[34:35], s[14:15], exec
	s_cselect_b32 s34, s61, s8
	s_add_i32 s34, s34, s83
	s_lshl_b32 s34, s34, 3
	s_add_i32 s34, s34, s84
	s_ashr_i32 s35, s34, 31
	s_lshl_b64 s[44:45], s[34:35], 15
	s_and_b64 s[34:35], s[16:17], exec
	s_cselect_b32 s34, s61, s8
	s_add_i32 s34, s34, s83
	s_lshl_b32 s34, s34, 3
	s_add_i32 s34, s34, s85
	s_add_i32 s8, s8, s83
	s_ashr_i32 s35, s34, 31
	s_lshl_b32 s39, s8, 3
	ds_read_b64_tr_b16 v[68:69], v149
	ds_read_b64_tr_b16 v[70:71], v149 offset:512
	ds_read_b64_tr_b16 v[64:65], v149 offset:4096
	ds_read_b64_tr_b16 v[66:67], v149 offset:4608
	s_waitcnt lgkmcnt(0)
	v_add_u32_e32 v179, v151, v135
	v_add_u32_e32 v181, v88, v139
	v_add_u32_e32 v183, v151, v139
	v_add_u32_e32 v185, v88, v140
	v_add_u32_e32 v187, v151, v140
	v_add_u32_e32 v189, v88, v141
	v_add_u32_e32 v191, v151, v141
	s_lshl_b64 s[52:53], s[34:35], 15
	s_add_i32 s34, s39, s86
	v_add_u32_e32 v178, v150, v135
	ds_read_b128 v[72:75], v177
	ds_read_b128 v[76:79], v178
	v_add_u32_e32 v180, v152, v135
	ds_read_b128 v[80:83], v179
	ds_read_b128 v[84:87], v180
	v_add_u32_e32 v182, v150, v139
	ds_read_b128 v[124:127], v181
	ds_read_b128 v[128:131], v182
	v_add_u32_e32 v184, v152, v139
	ds_read_b128 v[194:197], v183
	ds_read_b128 v[198:201], v184
	v_add_u32_e32 v186, v150, v140
	ds_read_b128 v[202:205], v185
	ds_read_b128 v[206:209], v186
	v_add_u32_e32 v188, v152, v140
	ds_read_b128 v[210:213], v187
	ds_read_b128 v[214:217], v188
	v_add_u32_e32 v190, v150, v141
	ds_read_b128 v[218:221], v189
	ds_read_b128 v[222:225], v190
	v_add_u32_e32 v192, v152, v141
	ds_read_b128 v[226:229], v191
	ds_read_b128 v[230:233], v192
	s_ashr_i32 s35, s34, 31
	s_lshl_b64 s[54:55], s[34:35], 15
	s_add_i32 s34, s39, s87
	s_ashr_i32 s35, s34, 31
	s_lshl_b64 s[56:57], s[34:35], 15
	s_add_i32 s61, s61, s83
	s_cmp_lt_u32 s1, s97
	v_cvt_pk_bf16_f32 v234, v0, v1
	v_cvt_pk_bf16_f32 v235, v2, v3
	v_cvt_pk_bf16_f32 v236, v4, v5
	v_cvt_pk_bf16_f32 v237, v6, v7
	s_waitcnt lgkmcnt(0)
	v_mfma_f32_16x16x32_bf16 v[72:75], v[234:237], v[72:75], 0
	v_mfma_f32_16x16x32_bf16 v[76:79], v[234:237], v[76:79], 0
	v_mfma_f32_16x16x32_bf16 v[80:83], v[234:237], v[80:83], 0
	v_mfma_f32_16x16x32_bf16 v[84:87], v[234:237], v[84:87], 0
	v_cvt_pk_bf16_f32 v234, v8, v9
	v_cvt_pk_bf16_f32 v235, v10, v11
	v_cvt_pk_bf16_f32 v236, v12, v13
	v_cvt_pk_bf16_f32 v237, v14, v15
	s_nop 0
	v_mfma_f32_16x16x32_bf16 v[72:75], v[234:237], v[124:127], v[72:75]
	v_cvt_pk_bf16_f32 v124, v16, v17
	v_cvt_pk_bf16_f32 v125, v18, v19
	v_cvt_pk_bf16_f32 v126, v20, v21
	v_mfma_f32_16x16x32_bf16 v[76:79], v[234:237], v[128:131], v[76:79]
	v_cvt_pk_bf16_f32 v127, v22, v23
	v_mfma_f32_16x16x32_bf16 v[80:83], v[234:237], v[194:197], v[80:83]
	v_mfma_f32_16x16x32_bf16 v[84:87], v[234:237], v[198:201], v[84:87]
	v_mfma_f32_16x16x32_bf16 v[72:75], v[124:127], v[202:205], v[72:75]
	v_mfma_f32_16x16x32_bf16 v[76:79], v[124:127], v[206:209], v[76:79]
	v_mfma_f32_16x16x32_bf16 v[80:83], v[124:127], v[210:213], v[80:83]
	v_mfma_f32_16x16x32_bf16 v[84:87], v[124:127], v[214:217], v[84:87]
	v_cvt_pk_bf16_f32 v124, v24, v25
	v_cvt_pk_bf16_f32 v125, v26, v27
	v_cvt_pk_bf16_f32 v126, v28, v29
	v_cvt_pk_bf16_f32 v127, v30, v31
	s_nop 0
	v_mfma_f32_16x16x32_bf16 v[72:75], v[124:127], v[218:221], v[72:75]
	v_mfma_f32_16x16x32_bf16 v[76:79], v[124:127], v[222:225], v[76:79]
	v_mfma_f32_16x16x32_bf16 v[80:83], v[124:127], v[226:229], v[80:83]
	v_mfma_f32_16x16x32_bf16 v[84:87], v[124:127], v[230:233], v[84:87]
	s_mov_b32 m0, s73
	v_lshl_add_u64 v[126:127], v[98:99], 0, s[44:45]
	s_waitcnt vmcnt(13) lgkmcnt(0)
	s_barrier
	global_load_lds_dwordx4 v[126:127], off
	v_lshl_add_u64 v[128:129], v[100:101], 0, s[52:53]
	s_mov_b32 m0, s74
	v_lshl_add_u32 v124, s61, 6, v148
	global_load_lds_dwordx4 v[128:129], off
	v_lshl_add_u64 v[130:131], v[98:99], 0, s[54:55]
	s_mov_b32 m0, s75
	v_ashrrev_i32_e32 v125, 31, v124
	global_load_lds_dwordx4 v[130:131], off
	v_lshl_add_u64 v[132:133], v[102:103], 0, s[56:57]
	s_mov_b32 m0, s76
	v_lshlrev_b64 v[124:125], 13, v[124:125]
	global_load_lds_dwordx4 v[132:133], off
	v_lshl_add_u64 v[124:125], v[118:119], 0, v[124:125]
	s_mov_b32 m0, s91
	s_nop 0
	global_load_lds_dwordx4 v[124:125], off
	v_lshl_add_u32 v124, s8, 6, v148
	v_ashrrev_i32_e32 v125, 31, v124
	v_lshlrev_b64 v[124:125], 13, v[124:125]
	v_lshl_add_u64 v[124:125], v[118:119], 0, v[124:125]
	s_mov_b32 m0, s92
	s_nop 0
	global_load_lds_dwordx4 v[124:125], off
	v_lshl_or_b32 v124, s60, 6, v138
	v_ashrrev_i32_e32 v125, 31, v124
	v_lshlrev_b64 v[124:125], 13, v[124:125]
	v_lshl_add_u64 v[124:125], v[122:123], 0, v[124:125]
	s_cbranch_scc1 .LBB0_687
	global_load_dwordx2 v[110:111], v[124:125], off
	v_lshl_add_u64 v[114:115], v[124:125], 0, s[36:37]
	global_load_dwordx2 v[112:113], v[114:115], off
	v_lshl_add_u64 v[116:117], v[124:125], 0, s[24:25]
	global_load_dwordx2 v[114:115], v[116:117], off
	v_lshl_add_u64 v[194:195], v[124:125], 0, s[22:23]
	global_load_dwordx2 v[116:117], v[194:195], off

; #define LAS __attribute__((address_space(3)))
; __global__ void __launch_bounds__(512) fwd_megakernel(Params p) {
;     extern __shared__ __attribute__((aligned(16))) unsigned char shm[];
;     cg::grid_group grid = cg::this_grid();
;     LAS unsigned char* lds = (LAS unsigned char*)shm;
;     pg8::StaticOrder S;
;     if (p.ph_hi > 1000) grid.sync();
;     if (threadIdx.x < 2) ((volatile LAS unsigned*)(lds + 157696))[threadIdx.x] = 0u;
;     __syncthreads();
;     XcdBarrier xb = xcd_barrier_post((unsigned*)(p.ws + OFF_SINK), (volatile LAS unsigned*)(lds + 157696));
	.amdhsa_kernel _Z14fwd_megakernel6Params
		.amdhsa_group_segment_fixed_size 0
		.amdhsa_private_segment_fixed_size 0
		.amdhsa_kernarg_size 400
		.amdhsa_user_sgpr_count 2
		.amdhsa_user_sgpr_dispatch_ptr 0
		.amdhsa_user_sgpr_queue_ptr 0
		.amdhsa_user_sgpr_kernarg_segment_ptr 1
		.amdhsa_user_sgpr_dispatch_id 0
		.amdhsa_user_sgpr_kernarg_preload_length 0
		.amdhsa_user_sgpr_kernarg_preload_offset 0
		.amdhsa_user_sgpr_private_segment_size 0
		.amdhsa_uses_dynamic_stack 0
		.amdhsa_enable_private_segment 0
		.amdhsa_system_sgpr_workgroup_id_x 1
		.amdhsa_system_sgpr_workgroup_id_y 0
		.amdhsa_system_sgpr_workgroup_id_z 0
		.amdhsa_system_sgpr_workgroup_info 0
		.amdhsa_system_vgpr_workitem_id 2
		.amdhsa_next_free_vgpr 250
		.amdhsa_next_free_sgpr 102
		.amdhsa_accum_offset 252
		.amdhsa_reserve_vcc 1
		.amdhsa_float_round_mode_32 0
		.amdhsa_float_round_mode_16_64 0
		.amdhsa_float_denorm_mode_32 3
		.amdhsa_float_denorm_mode_16_64 3
		.amdhsa_dx10_clamp 1
		.amdhsa_ieee_mode 1
		.amdhsa_fp16_overflow 0
		.amdhsa_tg_split 0
		.amdhsa_exception_fp_ieee_invalid_op 0
		.amdhsa_exception_fp_denorm_src 0
		.amdhsa_exception_fp_ieee_div_zero 0
		.amdhsa_exception_fp_ieee_overflow 0
		.amdhsa_exception_fp_ieee_underflow 0
		.amdhsa_exception_fp_ieee_inexact 0
		.amdhsa_exception_int_div_zero 0
	.end_amdhsa_kernel

; #define LAS __attribute__((address_space(3)))
; __global__ void __launch_bounds__(512) fwd_megakernel(Params p) {
;     extern __shared__ __attribute__((aligned(16))) unsigned char shm[];
;     cg::grid_group grid = cg::this_grid();
;     LAS unsigned char* lds = (LAS unsigned char*)shm;
;     pg8::StaticOrder S;
;     if (p.ph_hi > 1000) grid.sync();
;     if (threadIdx.x < 2) ((volatile LAS unsigned*)(lds + 157696))[threadIdx.x] = 0u;
;     __syncthreads();
;     XcdBarrier xb = xcd_barrier_post((unsigned*)(p.ws + OFF_SINK), (volatile LAS unsigned*)(lds + 157696));
amdhsa.kernels:
  - .agpr_count:     0
    .args:
      - .offset:         0
        .size:           144
        .value_kind:     by_value
      - .offset:         144
        .size:           4
        .value_kind:     hidden_block_count_x
      - .offset:         148
        .size:           4
        .value_kind:     hidden_block_count_y
      - .offset:         152
        .size:           4
        .value_kind:     hidden_block_count_z
      - .offset:         156
        .size:           2
        .value_kind:     hidden_group_size_x
      - .offset:         158
        .size:           2
        .value_kind:     hidden_group_size_y
      - .offset:         160
        .size:           2
        .value_kind:     hidden_group_size_z
      - .offset:         162
        .size:           2
        .value_kind:     hidden_remainder_x
      - .offset:         164
        .size:           2
        .value_kind:     hidden_remainder_y
      - .offset:         166
        .size:           2
        .value_kind:     hidden_remainder_z
      - .offset:         184
        .size:           8
        .value_kind:     hidden_global_offset_x
      - .offset:         192
        .size:           8
        .value_kind:     hidden_global_offset_y
      - .offset:         200
        .size:           8
        .value_kind:     hidden_global_offset_z
      - .offset:         208
        .size:           2
        .value_kind:     hidden_grid_dims
      - .offset:         232
        .size:           8
        .value_kind:     hidden_multigrid_sync_arg
      - .offset:         264
        .size:           4
        .value_kind:     hidden_dynamic_lds_size
    .group_segment_fixed_size: 0
    .kernarg_segment_align: 8
    .kernarg_segment_size: 400
    .language:       OpenCL C
    .language_version:
      - 2
      - 0
    .max_flat_workgroup_size: 512
    .name:           _Z14fwd_megakernel6Params
    .private_segment_fixed_size: 0
    .sgpr_count:     108
    .sgpr_spill_count: 10
    .symbol:         _Z14fwd_megakernel6Params.kd
    .uniform_work_group_size: 1
    .uses_dynamic_stack: false
    .vgpr_count:     250
    .vgpr_spill_count: 0
    .wavefront_size: 64
